# attention main loop: s_setprio 1 from the first (WAR) barrier instead of the second; s_setprio 0 before the back edge; on top of v41
# speedup vs baseline: 1.0260x; 1.0044x over previous
; __device__ __forceinline__ f32x4 mfma16(bf16x8 a, bf16x8 b, f32x4 c) { return __builtin_amdgcn_mfma_f32_16x16x32_bf16(a, b, c, 0, 0, 0); }
; __device__ __forceinline__ void attn_item(CParams& p, int j2, int b, int h, int q0row, int nkeys, bf16_t* smem) {
;     ...
;         lds_sync();
; #pragma unroll
;         for (int i = 0; i < 2; ++i) {
;             *(u32x4*)(sK + (srow + i * 32) * GST + skc) = rk[i];
;             *(u32x4*)(sV + (srow + i * 32) * GST + skc) = rv[i];
;         }
;         lds_sync();
;         {
;             const int t0 = (kt + 1 < nt ? kt + 1 : kt) << 6;
; #pragma unroll
;             for (int i = 0; i < 2; ++i) {
;                 rk[i] = *(const u32x4*)(Kb + (size_t)(t0 + srow + i * 32) * 128 + skc);
;                 rv[i] = *(const u32x4*)(Vb + (size_t)(srow + i * 32) * TALL + t0 + skc);
;             }
;         }
;         bf16x8 pf[2][4];
; #pragma unroll
;         for (int ih = 0; ih < 2; ++ih) {
;             f32x4 s[4][2];
; #pragma unroll
;             for (int tt = 0; tt < 4; ++tt)
; #pragma unroll
;                 for (int i = 0; i < 2; ++i) s[tt][i] = (f32x4){-mb, -mb, -mb, -mb};
; #pragma unroll
;             for (int ks = 0; ks < 2; ++ks)
; #pragma unroll
;                 for (int tt = 0; tt < 4; ++tt) {
;                     const bf16x8 kf = lds16(sK + (tt * 16 + l16) * GST + ks * 32 + quad * 8);
; #pragma unroll
;                     for (int i = 0; i < 2; ++i) s[tt][i] = mfma16(kf, qf[ih * 2 + i][ks], s[tt][i]);
;                 }
; #pragma unroll
;             for (int i = 0; i < 2; ++i) {
; #pragma unroll
;                 for (int tt = 0; tt < 4; ++tt) {
; #pragma unroll
;                     for (int r = 0; r < 4; ++r) s[tt][i][r] = __builtin_amdgcn_exp2f(s[tt][i][r]);
;                 }
; #pragma unroll
;                 for (int ksp = 0; ksp < 2; ++ksp) pf[ksp][ih * 2 + i] = pack8(s[2 * ksp][i], s[2 * ksp + 1][i]);
;             }
;         }
.LBB0_179:
	s_add_i32 s4, s9, 1
	s_waitcnt lgkmcnt(0)
	s_barrier
	s_setprio 1
	s_cmpk_lt_u32 s9, 0x83
	s_cselect_b32 s5, s4, s9
	s_lshl_b32 s6, s5, 6
	v_add_u32_e32 v188, s6, v176
	s_ashr_i32 s7, s6, 31
	v_add_u32_e32 v186, 32, v188
	v_lshl_add_u64 v[190:191], s[6:7], 1, v[180:181]
	v_ashrrev_i32_e32 v189, 31, v188
	v_ashrrev_i32_e32 v187, 31, v186
	s_cmpk_lg_i32 s4, 0x84
	s_mov_b32 s9, s4
	s_waitcnt vmcnt(3)
	ds_write_b128 v164, v[222:225]
	s_waitcnt vmcnt(2)
	ds_write_b128 v164, v[226:229] offset:9216
	s_waitcnt vmcnt(1)
	ds_write_b128 v164, v[230:233] offset:4608
	s_waitcnt vmcnt(0)
	ds_write_b128 v164, v[234:237] offset:13824
	s_waitcnt lgkmcnt(0)
	s_barrier
	ds_read_b128 v[148:151], v171 offset:4608
	ds_read_b128 v[156:159], v171 offset:4672
	ds_read_b128 v[136:139], v171
	ds_read_b128 v[132:135], v171 offset:64
	s_waitcnt lgkmcnt(3)
	v_mfma_f32_16x16x32_bf16 v[160:163], v[148:151], v[4:7], v[44:47]
	ds_read_b128 v[152:155], v171 offset:6912
	ds_read_b128 v[140:143], v171 offset:2304
	ds_read_b128 v[144:147], v171 offset:2368
	s_waitcnt lgkmcnt(5)
	v_mfma_f32_16x16x32_bf16 v[234:237], v[156:159], v[8:11], v[160:163]
	s_nop 2
	ds_read_b128 v[160:163], v171 offset:6976
	s_waitcnt lgkmcnt(5)
	v_mfma_f32_16x16x32_bf16 v[116:119], v[136:139], v[4:7], v[44:47]
	s_nop 1
	v_exp_f32_e32 v234, v234
	v_exp_f32_e32 v235, v235
	v_exp_f32_e32 v236, v236
	s_waitcnt lgkmcnt(3)
	v_mfma_f32_16x16x32_bf16 v[226:229], v[152:155], v[4:7], v[44:47]
	v_exp_f32_e32 v237, v237
	v_mfma_f32_16x16x32_bf16 v[120:123], v[136:139], v[12:15], v[44:47]
	s_waitcnt lgkmcnt(2)
	v_mfma_f32_16x16x32_bf16 v[124:127], v[140:143], v[4:7], v[44:47]
	v_mfma_f32_16x16x32_bf16 v[222:225], v[148:151], v[12:15], v[44:47]
	v_mfma_f32_16x16x32_bf16 v[230:233], v[152:155], v[12:15], v[44:47]
	v_mfma_f32_16x16x32_bf16 v[116:119], v[132:135], v[8:11], v[116:119]
	s_waitcnt lgkmcnt(0)
	v_mfma_f32_16x16x32_bf16 v[226:229], v[160:163], v[8:11], v[226:229]
	v_mfma_f32_16x16x32_bf16 v[128:131], v[140:143], v[12:15], v[44:47]
	s_nop 4
	v_exp_f32_e32 v118, v118
	v_exp_f32_e32 v119, v119
	v_exp_f32_e32 v226, v226
	v_mfma_f32_16x16x32_bf16 v[120:123], v[132:135], v[24:27], v[120:123]
	v_exp_f32_e32 v227, v227
	v_exp_f32_e32 v228, v228
	v_exp_f32_e32 v229, v229
	v_mfma_f32_16x16x32_bf16 v[124:127], v[144:147], v[8:11], v[124:127]
	v_exp_f32_e32 v116, v116
	v_exp_f32_e32 v117, v117
	s_nop 1
	v_exp_f32_e32 v120, v120
	v_mfma_f32_16x16x32_bf16 v[222:225], v[156:159], v[24:27], v[222:225]
	v_exp_f32_e32 v121, v121
	s_nop 0
	v_exp_f32_e32 v175, v124
	v_exp_f32_e32 v177, v125
	v_mfma_f32_16x16x32_bf16 v[230:233], v[160:163], v[24:27], v[230:233]
	v_cvt_pk_bf16_f32 v125, v118, v119
	v_cvt_pk_bf16_f32 v118, v226, v227
	v_cvt_pk_bf16_f32 v119, v228, v229
	v_mfma_f32_16x16x32_bf16 v[128:131], v[144:147], v[24:27], v[128:131]
	v_exp_f32_e32 v122, v122
	v_exp_f32_e32 v123, v123
	v_exp_f32_e32 v222, v222
	v_exp_f32_e32 v223, v223
	v_exp_f32_e32 v224, v224
	v_exp_f32_e32 v225, v225
	v_exp_f32_e32 v226, v230
	v_exp_f32_e32 v227, v231
	v_exp_f32_e32 v228, v232
	v_exp_f32_e32 v229, v233
	v_exp_f32_e32 v221, v126
	v_cvt_pk_bf16_f32 v124, v116, v117
	v_cvt_pk_bf16_f32 v126, v175, v177
	v_cvt_pk_bf16_f32 v116, v234, v235
	v_cvt_pk_bf16_f32 v117, v236, v237
	v_exp_f32_e32 v175, v128
	v_exp_f32_e32 v177, v129
	v_cvt_pk_bf16_f32 v128, v120, v121
	v_cvt_pk_bf16_f32 v129, v122, v123
	v_cvt_pk_bf16_f32 v120, v222, v223
	v_cvt_pk_bf16_f32 v121, v224, v225
	v_cvt_pk_bf16_f32 v122, v226, v227
	v_cvt_pk_bf16_f32 v123, v228, v229
	v_mfma_f32_16x16x32_bf16 v[222:225], v[136:139], v[28:31], v[44:47]
	v_exp_f32_e32 v127, v127
	v_exp_f32_e32 v131, v131
	v_cvt_pk_bf16_f32 v127, v221, v127
	v_mfma_f32_16x16x32_bf16 v[136:139], v[136:139], v[36:39], v[44:47]
	v_exp_f32_e32 v221, v130
	v_cvt_pk_bf16_f32 v130, v175, v177
	v_cvt_pk_bf16_f32 v131, v221, v131
	v_mfma_f32_16x16x32_bf16 v[226:229], v[140:143], v[28:31], v[44:47]
	v_mfma_f32_16x16x32_bf16 v[140:143], v[140:143], v[36:39], v[44:47]
	v_mfma_f32_16x16x32_bf16 v[230:233], v[148:151], v[28:31], v[44:47]
	v_mfma_f32_16x16x32_bf16 v[148:151], v[148:151], v[36:39], v[44:47]
	v_mfma_f32_16x16x32_bf16 v[234:237], v[152:155], v[28:31], v[44:47]
	v_mfma_f32_16x16x32_bf16 v[152:155], v[152:155], v[36:39], v[44:47]
	v_mfma_f32_16x16x32_bf16 v[222:225], v[132:135], v[32:35], v[222:225]
	v_mfma_f32_16x16x32_bf16 v[136:139], v[132:135], v[40:43], v[136:139]
	v_mfma_f32_16x16x32_bf16 v[132:135], v[144:147], v[32:35], v[226:229]
	v_mfma_f32_16x16x32_bf16 v[144:147], v[144:147], v[40:43], v[140:143]
	s_nop 5
	v_exp_f32_e32 v138, v138
	v_exp_f32_e32 v134, v134
	v_exp_f32_e32 v135, v135
	v_mfma_f32_16x16x32_bf16 v[140:143], v[156:159], v[32:35], v[230:233]
	v_exp_f32_e32 v139, v139
	v_exp_f32_e32 v136, v136
	v_exp_f32_e32 v137, v137
	v_mfma_f32_16x16x32_bf16 v[148:151], v[156:159], v[40:43], v[148:151]
	v_exp_f32_e32 v132, v132
	v_exp_f32_e32 v133, v133
	v_exp_f32_e32 v147, v147
	v_mfma_f32_16x16x32_bf16 v[156:159], v[160:163], v[32:35], v[234:237]
	v_exp_f32_e32 v175, v140
	s_nop 2
	v_exp_f32_e32 v148, v148
	v_exp_f32_e32 v149, v149
	v_mfma_f32_16x16x32_bf16 v[152:155], v[160:163], v[40:43], v[152:155]
	v_exp_f32_e32 v150, v150
	v_exp_f32_e32 v156, v156
	v_exp_f32_e32 v157, v157
	v_exp_f32_e32 v151, v151
	v_exp_f32_e32 v160, v222
	s_nop 2
	v_exp_f32_e32 v154, v154
	v_exp_f32_e32 v155, v155
	v_exp_f32_e32 v222, v143
	v_cvt_pk_bf16_f32 v143, v134, v135
	v_cvt_pk_bf16_f32 v134, v156, v157
	v_exp_f32_e32 v157, v145
	v_cvt_pk_bf16_f32 v145, v138, v139
	v_cvt_pk_bf16_f32 v139, v154, v155
	v_add_u32_e32 v154, 0x2000, v173
	v_exp_f32_e32 v158, v158
	v_exp_f32_e32 v159, v159
	v_exp_f32_e32 v156, v144
; __device__ __forceinline__ f32x4 mfma16(bf16x8 a, bf16x8 b, f32x4 c) { return __builtin_amdgcn_mfma_f32_16x16x32_bf16(a, b, c, 0, 0, 0); }
; __device__ __forceinline__ void attn_item(CParams& p, int j2, int b, int h, int q0row, int nkeys, bf16_t* smem) {
;     ...
;             const int t0 = (kt + 1 < nt ? kt + 1 : kt) << 6;
; #pragma unroll
;             for (int i = 0; i < 2; ++i) {
;                 rk[i] = *(const u32x4*)(Kb + (size_t)(t0 + srow + i * 32) * 128 + skc);
;                 rv[i] = *(const u32x4*)(Vb + (size_t)(srow + i * 32) * TALL + t0 + skc);
;             }
;         }
;         bf16x8 pf[2][4];
; #pragma unroll
;         for (int ih = 0; ih < 2; ++ih) {
;             f32x4 s[4][2];
; #pragma unroll
;             for (int tt = 0; tt < 4; ++tt)
; #pragma unroll
;                 for (int i = 0; i < 2; ++i) s[tt][i] = (f32x4){-mb, -mb, -mb, -mb};
; #pragma unroll
;             for (int ks = 0; ks < 2; ++ks)
; #pragma unroll
;                 for (int tt = 0; tt < 4; ++tt) {
;                     const bf16x8 kf = lds16(sK + (tt * 16 + l16) * GST + ks * 32 + quad * 8);
; #pragma unroll
;                     for (int i = 0; i < 2; ++i) s[tt][i] = mfma16(kf, qf[ih * 2 + i][ks], s[tt][i]);
;                 }
; #pragma unroll
;             for (int i = 0; i < 2; ++i) {
; #pragma unroll
;                 for (int tt = 0; tt < 4; ++tt) {
; #pragma unroll
;                     for (int r = 0; r < 4; ++r) s[tt][i][r] = __builtin_amdgcn_exp2f(s[tt][i][r]);
;                 }
; #pragma unroll
;                 for (int ksp = 0; ksp < 2; ++ksp) pf[ksp][ih * 2 + i] = pack8(s[2 * ksp][i], s[2 * ksp + 1][i]);
;             }
;         }
; #pragma unroll
;         for (int ksp = 0; ksp < 2; ++ksp)
; #pragma unroll
;             for (int d = 0; d < 5; ++d) {
;                 const bf16_t* vp = sV + (d * 16 + l16) * GST + ksp * 32 + quad * 4;
;                 const bf16x8 vf = lds8x2(vp, vp + 16);
; #pragma unroll
;                 for (int i = 0; i < 4; ++i) o[d][i] = mfma16(vf, pf[ksp][i], o[d][i]);
;             }
	v_cvt_pk_bf16_f32 v144, v136, v137
	v_cvt_pk_bf16_f32 v136, v148, v149
	v_cvt_pk_bf16_f32 v137, v150, v151
	ds_read2_b64 v[148:151], v154 offset0:128 offset1:132
	v_exp_f32_e32 v161, v223
	v_exp_f32_e32 v162, v224
	v_exp_f32_e32 v163, v225
	v_cvt_pk_bf16_f32 v135, v158, v159
	v_exp_f32_e32 v158, v146
	v_exp_f32_e32 v152, v152
	v_exp_f32_e32 v153, v153
	v_exp_f32_e32 v177, v141
	v_exp_f32_e32 v221, v142
	v_cvt_pk_bf16_f32 v140, v160, v161
	v_cvt_pk_bf16_f32 v141, v162, v163
	v_cvt_pk_bf16_f32 v142, v132, v133
	v_cvt_pk_bf16_f32 v146, v156, v157
	v_cvt_pk_bf16_f32 v147, v158, v147
	v_cvt_pk_bf16_f32 v138, v152, v153
	v_cvt_pk_bf16_f32 v132, v175, v177
	v_cvt_pk_bf16_f32 v133, v221, v222
	v_add_u32_e32 v152, 0x2800, v173
	v_add_u32_e32 v153, 0x3000, v173
	ds_read2_b64 v[160:163], v152 offset0:160 offset1:164
	v_add_u32_e32 v155, 0x3800, v173
	ds_read2_b64 v[156:159], v153 offset0:192 offset1:196
	v_add_u32_e32 v175, 0x4800, v173
	v_lshlrev_b64 v[222:223], 8, v[188:189]
	v_lshl_add_u64 v[222:223], v[178:179], 0, v[222:223]
	v_lshl_add_u64 v[226:227], v[190:191], 0, v[182:183]
	global_load_dwordx4 v[222:225], v[222:223], off
	v_lshlrev_b64 v[230:231], 8, v[186:187]
	global_load_dwordx4 v[226:229], v[226:227], off
	v_lshl_add_u64 v[230:231], v[178:179], 0, v[230:231]
	v_lshl_add_u64 v[234:235], v[190:191], 0, v[184:185]
	global_load_dwordx4 v[230:233], v[230:231], off
	global_load_dwordx4 v[234:237], v[234:235], off
	s_waitcnt lgkmcnt(2)
	v_mfma_f32_16x16x32_bf16 v[112:115], v[148:151], v[124:127], v[112:115]
	v_mfma_f32_16x16x32_bf16 v[108:111], v[148:151], v[128:131], v[108:111]
	v_mfma_f32_16x16x32_bf16 v[100:103], v[148:151], v[140:143], v[100:103]
	v_mfma_f32_16x16x32_bf16 v[80:83], v[148:151], v[144:147], v[80:83]
	ds_read2_b64 v[148:151], v155 offset0:224 offset1:228
	s_waitcnt lgkmcnt(2)
	v_mfma_f32_16x16x32_bf16 v[96:99], v[160:163], v[124:127], v[96:99]
	v_mfma_f32_16x16x32_bf16 v[76:79], v[160:163], v[128:131], v[76:79]
	v_mfma_f32_16x16x32_bf16 v[60:63], v[160:163], v[140:143], v[60:63]
	v_mfma_f32_16x16x32_bf16 v[20:23], v[160:163], v[144:147], v[20:23]
	ds_read2_b64 v[160:163], v175 offset1:4
	s_waitcnt lgkmcnt(2)
	v_mfma_f32_16x16x32_bf16 v[88:91], v[156:159], v[124:127], v[88:91]
	v_mfma_f32_16x16x32_bf16 v[68:71], v[156:159], v[128:131], v[68:71]
	v_mfma_f32_16x16x32_bf16 v[52:55], v[156:159], v[140:143], v[52:55]
	v_mfma_f32_16x16x32_bf16 v[0:3], v[156:159], v[144:147], v[0:3]
	ds_read2_b64 v[156:159], v154 offset0:136 offset1:140
	s_waitcnt lgkmcnt(2)
	v_mfma_f32_16x16x32_bf16 v[92:95], v[148:151], v[124:127], v[92:95]
	v_mfma_f32_16x16x32_bf16 v[72:75], v[148:151], v[128:131], v[72:75]
	v_mfma_f32_16x16x32_bf16 v[56:59], v[148:151], v[140:143], v[56:59]
	v_mfma_f32_16x16x32_bf16 v[16:19], v[148:151], v[144:147], v[16:19]
	ds_read2_b64 v[148:151], v152 offset0:168 offset1:172
	s_waitcnt lgkmcnt(2)
	v_mfma_f32_16x16x32_bf16 v[104:107], v[160:163], v[124:127], v[104:107]
	v_mfma_f32_16x16x32_bf16 v[84:87], v[160:163], v[128:131], v[84:87]
	v_mfma_f32_16x16x32_bf16 v[64:67], v[160:163], v[140:143], v[64:67]
	v_mfma_f32_16x16x32_bf16 v[48:51], v[160:163], v[144:147], v[48:51]
	ds_read2_b64 v[160:163], v153 offset0:200 offset1:204
	s_waitcnt lgkmcnt(2)
	v_mfma_f32_16x16x32_bf16 v[112:115], v[156:159], v[116:119], v[112:115]
	v_mfma_f32_16x16x32_bf16 v[108:111], v[156:159], v[120:123], v[108:111]
	v_mfma_f32_16x16x32_bf16 v[100:103], v[156:159], v[132:135], v[100:103]
	v_mfma_f32_16x16x32_bf16 v[80:83], v[156:159], v[136:139], v[80:83]
	ds_read2_b64 v[156:159], v155 offset0:232 offset1:236
	s_waitcnt lgkmcnt(2)
	v_mfma_f32_16x16x32_bf16 v[96:99], v[148:151], v[116:119], v[96:99]
	v_mfma_f32_16x16x32_bf16 v[76:79], v[148:151], v[120:123], v[76:79]
	v_mfma_f32_16x16x32_bf16 v[60:63], v[148:151], v[132:135], v[60:63]
	v_mfma_f32_16x16x32_bf16 v[20:23], v[148:151], v[136:139], v[20:23]
	ds_read2_b64 v[148:151], v175 offset0:8 offset1:12
	s_waitcnt lgkmcnt(2)
	v_mfma_f32_16x16x32_bf16 v[88:91], v[160:163], v[116:119], v[88:91]
	v_mfma_f32_16x16x32_bf16 v[68:71], v[160:163], v[120:123], v[68:71]
	v_mfma_f32_16x16x32_bf16 v[52:55], v[160:163], v[132:135], v[52:55]
	v_mfma_f32_16x16x32_bf16 v[0:3], v[160:163], v[136:139], v[0:3]
	s_waitcnt lgkmcnt(1)
	v_mfma_f32_16x16x32_bf16 v[92:95], v[156:159], v[116:119], v[92:95]
	v_mfma_f32_16x16x32_bf16 v[72:75], v[156:159], v[120:123], v[72:75]
	v_mfma_f32_16x16x32_bf16 v[56:59], v[156:159], v[132:135], v[56:59]
	v_mfma_f32_16x16x32_bf16 v[16:19], v[156:159], v[136:139], v[16:19]
	s_waitcnt lgkmcnt(0)
	v_mfma_f32_16x16x32_bf16 v[104:107], v[148:151], v[116:119], v[104:107]
	v_mfma_f32_16x16x32_bf16 v[84:87], v[148:151], v[120:123], v[84:87]
	v_mfma_f32_16x16x32_bf16 v[64:67], v[148:151], v[132:135], v[64:67]
	v_mfma_f32_16x16x32_bf16 v[48:51], v[148:151], v[136:139], v[48:51]
	s_setprio 0
	s_cbranch_scc1 .LBB0_179
; __device__ __forceinline__ void attn_item(CParams& p, int j2, int b, int h, int q0row, int nkeys, bf16_t* smem) {
;     ...
;     bf16_t* as = (bf16_t*)(p.ws + WS_AS);
; #pragma unroll
;     for (int i = 0; i < 4; ++i) {
;         const float l = __shfl(o[4][i][0], l16);
;         const float inv = 1.f / l;
;         const int row = q0row + wave * 64 + i * 16 + l16;
; #pragma unroll
;         for (int d = 0; d < 4; ++d)
;             st4bf(as + frag_off(row, h * 64 + d * 16 + quad * 4, 1024), o[d][i][0] * inv, o[d][i][1] * inv, o[d][i][2] * inv, o[d][i][3] * inv);
;     }
	s_waitcnt vmcnt(0)
	v_and_or_b32 v4, v197, 64, v220
	v_lshlrev_b32_e32 v14, 2, v4
	s_nop 1
	ds_bpermute_b32 v4, v14, v104
	v_and_or_b32 v7, v169, 16, v220
	s_lshl_b32 s78, s8, 11
	v_lshlrev_b32_e32 v164, 4, v7
	s_mov_b32 s39, s0
	s_waitcnt lgkmcnt(0)
	v_div_scale_f32 v5, s[4:5], v4, v4, 1.0
	v_rcp_f32_e32 v6, v5
	s_nop 0
	v_fma_f32 v8, -v5, v6, 1.0
	v_fmac_f32_e32 v6, v8, v6
	v_div_scale_f32 v8, vcc, 1.0, v4, 1.0
	v_mul_f32_e32 v9, v8, v6
	v_fma_f32 v10, -v5, v9, v8
	v_fmac_f32_e32 v9, v10, v6
	v_fma_f32 v5, -v5, v9, v8
	v_div_fmas_f32 v5, v5, v6, v9
	v_div_fixup_f32 v6, v5, v4, 1.0
	v_ashrrev_i32_e32 v4, 4, v219
	v_ashrrev_i32_e32 v5, 31, v4
	v_lshlrev_b64 v[4:5], 15, v[4:5]
	v_lshl_add_u64 v[4:5], s[50:51], 0, v[4:5]
	v_lshl_add_u64 v[4:5], v[4:5], 0, s[78:79]
	v_lshl_add_u64 v[8:9], v[4:5], 0, v[164:165]
	v_and_b32_e32 v4, 8, v169
	v_mov_b32_e32 v5, v165
	v_pk_mul_f32 v[10:11], v[112:113], v[6:7] op_sel_hi:[1,0]
	v_pk_mul_f32 v[12:13], v[114:115], v[6:7] op_sel_hi:[1,0]
	v_lshl_add_u64 v[8:9], v[8:9], 0, v[4:5]
	v_cvt_pk_bf16_f32 v10, v10, v11
	v_cvt_pk_bf16_f32 v11, v12, v13
	global_store_dwordx2 v[8:9], v[10:11], off
	v_pk_mul_f32 v[10:11], v[96:97], v[6:7] op_sel_hi:[1,0]
	v_pk_mul_f32 v[12:13], v[98:99], v[6:7] op_sel_hi:[1,0]
	v_cvt_pk_bf16_f32 v10, v10, v11
	v_cvt_pk_bf16_f32 v11, v12, v13
	global_store_dwordx2 v[8:9], v[10:11], off offset:512
	v_pk_mul_f32 v[10:11], v[88:89], v[6:7] op_sel_hi:[1,0]
	v_pk_mul_f32 v[12:13], v[90:91], v[6:7] op_sel_hi:[1,0]
	v_cvt_pk_bf16_f32 v10, v10, v11
	v_cvt_pk_bf16_f32 v11, v12, v13
	global_store_dwordx2 v[8:9], v[10:11], off offset:1024
	v_pk_mul_f32 v[10:11], v[92:93], v[6:7] op_sel_hi:[1,0]
	v_pk_mul_f32 v[6:7], v[94:95], v[6:7] op_sel_hi:[1,0]
	v_cvt_pk_bf16_f32 v10, v10, v11
	v_cvt_pk_bf16_f32 v11, v6, v7
	ds_bpermute_b32 v6, v14, v84
	global_store_dwordx2 v[8:9], v[10:11], off offset:1536
	s_waitcnt lgkmcnt(0)
	v_div_scale_f32 v7, s[4:5], v6, v6, 1.0
	v_rcp_f32_e32 v8, v7
	s_nop 0
	v_fma_f32 v9, -v7, v8, 1.0
	v_fmac_f32_e32 v8, v9, v8
	v_div_scale_f32 v9, vcc, 1.0, v6, 1.0
	v_mul_f32_e32 v10, v9, v8
	v_fma_f32 v11, -v7, v10, v9
	v_fmac_f32_e32 v10, v11, v8
	v_fma_f32 v7, -v7, v10, v9
	v_div_fmas_f32 v7, v7, v8, v10
	v_ashrrev_i32_e32 v8, 4, v174
	v_ashrrev_i32_e32 v9, 31, v8
	v_lshlrev_b64 v[8:9], 15, v[8:9]
	v_lshl_add_u64 v[8:9], s[50:51], 0, v[8:9]
	v_div_fixup_f32 v6, v7, v6, 1.0
	v_lshl_add_u64 v[8:9], v[8:9], 0, s[78:79]
	v_lshl_add_u64 v[8:9], v[8:9], 0, v[164:165]
	v_pk_mul_f32 v[10:11], v[108:109], v[6:7] op_sel_hi:[1,0]
	v_pk_mul_f32 v[12:13], v[110:111], v[6:7] op_sel_hi:[1,0]
	v_lshl_add_u64 v[8:9], v[8:9], 0, v[4:5]
	v_cvt_pk_bf16_f32 v10, v10, v11
	v_cvt_pk_bf16_f32 v11, v12, v13
	global_store_dwordx2 v[8:9], v[10:11], off
	v_pk_mul_f32 v[10:11], v[76:77], v[6:7] op_sel_hi:[1,0]
	v_pk_mul_f32 v[12:13], v[78:79], v[6:7] op_sel_hi:[1,0]
	v_cvt_pk_bf16_f32 v10, v10, v11
	v_cvt_pk_bf16_f32 v11, v12, v13
	global_store_dwordx2 v[8:9], v[10:11], off offset:512
	v_pk_mul_f32 v[10:11], v[68:69], v[6:7] op_sel_hi:[1,0]
	v_pk_mul_f32 v[12:13], v[70:71], v[6:7] op_sel_hi:[1,0]
	v_cvt_pk_bf16_f32 v10, v10, v11
	v_cvt_pk_bf16_f32 v11, v12, v13
	global_store_dwordx2 v[8:9], v[10:11], off offset:1024
	v_pk_mul_f32 v[10:11], v[72:73], v[6:7] op_sel_hi:[1,0]
	v_pk_mul_f32 v[6:7], v[74:75], v[6:7] op_sel_hi:[1,0]
	v_cvt_pk_bf16_f32 v10, v10, v11
	v_cvt_pk_bf16_f32 v11, v6, v7
	ds_bpermute_b32 v6, v14, v64
	global_store_dwordx2 v[8:9], v[10:11], off offset:1536
	s_waitcnt lgkmcnt(0)
	v_div_scale_f32 v7, s[4:5], v6, v6, 1.0
	v_rcp_f32_e32 v8, v7
	s_nop 0
	v_fma_f32 v9, -v7, v8, 1.0
	v_fmac_f32_e32 v8, v9, v8
	v_div_scale_f32 v9, vcc, 1.0, v6, 1.0
	v_mul_f32_e32 v10, v9, v8
	v_fma_f32 v11, -v7, v10, v9
	v_fmac_f32_e32 v10, v11, v8
	v_fma_f32 v7, -v7, v10, v9
	v_div_fmas_f32 v7, v7, v8, v10
	v_ashrrev_i32_e32 v8, 4, v172
	v_ashrrev_i32_e32 v9, 31, v8
	v_lshlrev_b64 v[8:9], 15, v[8:9]
	v_lshl_add_u64 v[8:9], s[50:51], 0, v[8:9]
	v_div_fixup_f32 v6, v7, v6, 1.0
	v_lshl_add_u64 v[8:9], v[8:9], 0, s[78:79]
	v_lshl_add_u64 v[8:9], v[8:9], 0, v[164:165]
	v_pk_mul_f32 v[10:11], v[100:101], v[6:7] op_sel_hi:[1,0]
	v_pk_mul_f32 v[12:13], v[102:103], v[6:7] op_sel_hi:[1,0]
	v_lshl_add_u64 v[8:9], v[8:9], 0, v[4:5]
	v_cvt_pk_bf16_f32 v10, v10, v11
	v_cvt_pk_bf16_f32 v11, v12, v13
	global_store_dwordx2 v[8:9], v[10:11], off
	v_pk_mul_f32 v[10:11], v[60:61], v[6:7] op_sel_hi:[1,0]
	v_pk_mul_f32 v[12:13], v[62:63], v[6:7] op_sel_hi:[1,0]
	v_cvt_pk_bf16_f32 v10, v10, v11
	v_cvt_pk_bf16_f32 v11, v12, v13
	global_store_dwordx2 v[8:9], v[10:11], off offset:512
	v_pk_mul_f32 v[10:11], v[52:53], v[6:7] op_sel_hi:[1,0]
	v_pk_mul_f32 v[12:13], v[54:55], v[6:7] op_sel_hi:[1,0]
	v_cvt_pk_bf16_f32 v10, v10, v11
	v_cvt_pk_bf16_f32 v11, v12, v13
	global_store_dwordx2 v[8:9], v[10:11], off offset:1024
	v_pk_mul_f32 v[10:11], v[56:57], v[6:7] op_sel_hi:[1,0]
	v_pk_mul_f32 v[6:7], v[58:59], v[6:7] op_sel_hi:[1,0]
	v_cvt_pk_bf16_f32 v10, v10, v11
	v_cvt_pk_bf16_f32 v11, v6, v7
	ds_bpermute_b32 v6, v14, v48
	global_store_dwordx2 v[8:9], v[10:11], off offset:1536
	s_waitcnt lgkmcnt(0)
	v_div_scale_f32 v7, s[4:5], v6, v6, 1.0
	v_rcp_f32_e32 v8, v7
	s_nop 0
	v_fma_f32 v9, -v7, v8, 1.0
	v_fmac_f32_e32 v8, v9, v8
	v_div_scale_f32 v9, vcc, 1.0, v6, 1.0
	v_mul_f32_e32 v10, v9, v8
	v_fma_f32 v11, -v7, v10, v9
	v_fmac_f32_e32 v10, v11, v8
	v_fma_f32 v7, -v7, v10, v9
	v_div_fmas_f32 v7, v7, v8, v10
	v_ashrrev_i32_e32 v8, 4, v170
	v_ashrrev_i32_e32 v9, 31, v8
	v_lshlrev_b64 v[8:9], 15, v[8:9]
	v_lshl_add_u64 v[8:9], s[50:51], 0, v[8:9]
	v_lshl_add_u64 v[8:9], v[8:9], 0, s[78:79]
	v_div_fixup_f32 v6, v7, v6, 1.0
	v_lshl_add_u64 v[8:9], v[8:9], 0, v[164:165]
	v_lshl_add_u64 v[4:5], v[8:9], 0, v[4:5]
	v_pk_mul_f32 v[8:9], v[80:81], v[6:7] op_sel_hi:[1,0]
	v_pk_mul_f32 v[10:11], v[82:83], v[6:7] op_sel_hi:[1,0]
	v_pk_mul_f32 v[0:1], v[0:1], v[6:7] op_sel_hi:[1,0]
	v_pk_mul_f32 v[2:3], v[2:3], v[6:7] op_sel_hi:[1,0]
	v_cvt_pk_bf16_f32 v8, v8, v9
	v_cvt_pk_bf16_f32 v9, v10, v11
	v_cvt_pk_bf16_f32 v0, v0, v1
	v_cvt_pk_bf16_f32 v1, v2, v3
	global_store_dwordx2 v[4:5], v[8:9], off
	v_pk_mul_f32 v[8:9], v[20:21], v[6:7] op_sel_hi:[1,0]
	v_pk_mul_f32 v[10:11], v[22:23], v[6:7] op_sel_hi:[1,0]
	global_store_dwordx2 v[4:5], v[0:1], off offset:1024
	v_pk_mul_f32 v[0:1], v[16:17], v[6:7] op_sel_hi:[1,0]
	v_pk_mul_f32 v[2:3], v[18:19], v[6:7] op_sel_hi:[1,0]
	v_cvt_pk_bf16_f32 v8, v8, v9
	v_cvt_pk_bf16_f32 v9, v10, v11
	v_cvt_pk_bf16_f32 v0, v0, v1
	v_cvt_pk_bf16_f32 v1, v2, v3
	global_store_dwordx2 v[4:5], v[8:9], off offset:512
	global_store_dwordx2 v[4:5], v[0:1], off offset:1536
	s_branch .LBB0_166
